# band softmax: exp via fmamk (one VALU less per element), row max via permlane16/32 swap instead of ds_bpermute
# speedup vs baseline: 1.0126x; 1.0005x over previous
; __device__ __forceinline__ f32x4 mfma16(bf16x8 a, bf16x8 b, f32x4 c) { return __builtin_amdgcn_mfma_f32_16x16x32_bf16(a, b, c, 0, 0, 0); }
; __device__ __forceinline__ void b_item(const Params& P, int layer, LAS unsigned char* lds, int item, int tid) {
;     ...
;                 mt = fmaxf(mt, __shfl_xor(mt, 16)); mt = fmaxf(mt, __shfl_xor(mt, 32));
;                 const float mn = fmaxf(mrun[u], mt); alpha[u] = __expf(mrun[u] - mn); mrun[u] = mn;
;                 float ls = 0.f;
; #pragma unroll
;                 for (int sb = 0; sb < 4; ++sb)
; #pragma unroll
;                     for (int r = 0; r < 4; ++r) { const float pe = __expf(accs[u][sb][r] - mn); accs[u][sb][r] = pe; ls += pe; }
;                 lrun[u] = lrun[u] * alpha[u] + ls;
;                 pf[u][0] = pack8(accs[u][0], accs[u][1]); pf[u][1] = pack8(accs[u][2], accs[u][3]); }
;             __builtin_amdgcn_s_setprio(1);
; #pragma unroll
;             for (int vb = 0; vb < 8; ++vb) { acco[0][vb] = acco[0][vb] * alpha[0]; acco[1][vb] = acco[1][vb] * alpha[1];
; #pragma unroll
;                 for (int ks = 0; ks < 2; ++ks) { const bf16x8 vf = tr_frag_a<true>(Vt, vaddr[vb], ks);
;                     acco[0][vb] = mfma16(vf, pf[0][ks], acco[0][vb]); acco[1][vb] = mfma16(vf, pf[1][ks], acco[1][vb]); } }
.LBB0_159:
	s_or_b64 exec, exec, s[0:1]
	s_waitcnt lgkmcnt(0)
	v_max3_f32 v81, v227, v80, v81
	v_mul_f32_e32 v244, 0xbfb8aa3b, v81
	v_fmamk_f32 v69, v92, 0x3fb8aa3b, v244
	v_exp_f32_e32 v70, v69
	v_fmamk_f32 v69, v93, 0x3fb8aa3b, v244
	v_exp_f32_e32 v71, v69
	v_fmamk_f32 v69, v94, 0x3fb8aa3b, v244
	v_sub_f32_e32 v64, v227, v81
	v_mul_f32_e32 v64, 0x3fb8aa3b, v64
	v_exp_f32_e32 v92, v69
	v_fmamk_f32 v69, v95, 0x3fb8aa3b, v244
	v_exp_f32_e32 v80, v64
	v_fmamk_f32 v64, v164, 0x3fb8aa3b, v244
	v_fmamk_f32 v65, v165, 0x3fb8aa3b, v244
	v_exp_f32_e32 v93, v69
	v_fmamk_f32 v69, v88, 0x3fb8aa3b, v244
	v_exp_f32_e32 v64, v64
	v_fmamk_f32 v66, v166, 0x3fb8aa3b, v244
	v_exp_f32_e32 v65, v65
	v_fmamk_f32 v67, v167, 0x3fb8aa3b, v244
	v_exp_f32_e32 v88, v69
	v_fmamk_f32 v69, v89, 0x3fb8aa3b, v244
	v_exp_f32_e32 v66, v66
	v_exp_f32_e32 v67, v67
	v_exp_f32_e32 v89, v69
	v_fmamk_f32 v69, v90, 0x3fb8aa3b, v244
	v_add_f32_e32 v68, 0, v64
	v_add_f32_e32 v68, v65, v68
	v_exp_f32_e32 v90, v69
	v_fmamk_f32 v69, v91, 0x3fb8aa3b, v244
	v_add_f32_e32 v68, v66, v68
	v_add_f32_e32 v68, v67, v68
	v_exp_f32_e32 v91, v69
	v_fmamk_f32 v69, v84, 0x3fb8aa3b, v244
	v_add_f32_e32 v68, v70, v68
	v_add_f32_e32 v68, v71, v68
	v_exp_f32_e32 v84, v69
	v_fmamk_f32 v69, v85, 0x3fb8aa3b, v244
	v_add_f32_e32 v68, v92, v68
	v_add_f32_e32 v68, v93, v68
	v_exp_f32_e32 v85, v69
	v_fmamk_f32 v69, v86, 0x3fb8aa3b, v244
	v_add_f32_e32 v68, v88, v68
	v_add_f32_e32 v68, v89, v68
	v_exp_f32_e32 v86, v69
	v_fmamk_f32 v69, v87, 0x3fb8aa3b, v244
	v_add_f32_e32 v68, v90, v68
	v_mov_b32_e32 v82, v229
	v_mov_b32_e32 v240, v229
	s_nop 1
	v_permlane16_swap_b32 v82, v240
	v_max_f32_e32 v82, v82, v240
	v_add_f32_e32 v68, v91, v68
	v_exp_f32_e32 v87, v69
	v_add_f32_e32 v68, v84, v68
	v_add_f32_e32 v68, v85, v68
	v_add_f32_e32 v68, v86, v68
	v_add_f32_e32 v83, v87, v68
	v_cvt_pk_bf16_f32 v68, v64, v65
	v_cvt_pk_bf16_f32 v70, v70, v71
	v_cvt_pk_bf16_f32 v71, v92, v93
	v_mov_b32_e32 v92, v82
	v_mov_b32_e32 v240, v82
	s_nop 1
	v_permlane32_swap_b32 v92, v240
	v_max_f32_e32 v92, v92, v240
	v_cvt_pk_bf16_f32 v69, v66, v67
	v_cvt_pk_bf16_f32 v66, v84, v85
	v_cvt_pk_bf16_f32 v67, v86, v87
	v_cvt_pk_bf16_f32 v64, v88, v89
	v_max3_f32 v84, v226, v82, v92
	v_mul_f32_e32 v245, 0xbfb8aa3b, v84
	v_fmamk_f32 v85, v168, 0x3fb8aa3b, v245
	v_exp_f32_e32 v86, v85
	v_fmamk_f32 v85, v169, 0x3fb8aa3b, v245
	v_exp_f32_e32 v87, v85
	v_fmamk_f32 v85, v170, 0x3fb8aa3b, v245
	v_fmamk_f32 v76, v76, 0x3fb8aa3b, v245
	v_cvt_pk_bf16_f32 v65, v90, v91
	v_exp_f32_e32 v88, v85
	v_fmamk_f32 v85, v171, 0x3fb8aa3b, v245
	v_exp_f32_e32 v90, v76
	v_fmamk_f32 v76, v77, 0x3fb8aa3b, v245
	v_exp_f32_e32 v89, v85
	v_exp_f32_e32 v91, v76
	v_fmamk_f32 v76, v78, 0x3fb8aa3b, v245
	v_add_f32_e32 v85, 0, v86
	v_add_f32_e32 v85, v87, v85
	v_exp_f32_e32 v92, v76
	v_fmamk_f32 v76, v79, 0x3fb8aa3b, v245
	v_add_f32_e32 v85, v88, v85
	v_fmamk_f32 v72, v72, 0x3fb8aa3b, v245
	v_add_f32_e32 v85, v89, v85
	v_exp_f32_e32 v79, v76
	v_fmamk_f32 v73, v73, 0x3fb8aa3b, v245
	v_fmamk_f32 v77, v172, 0x3fb8aa3b, v245
	v_add_f32_e32 v76, v90, v85
	v_exp_f32_e32 v72, v72
	v_fmamk_f32 v74, v74, 0x3fb8aa3b, v245
	v_add_f32_e32 v76, v91, v76
	v_exp_f32_e32 v73, v73
	v_fmamk_f32 v75, v75, 0x3fb8aa3b, v245
	v_exp_f32_e32 v93, v77
	v_fmamk_f32 v77, v173, 0x3fb8aa3b, v245
	v_add_f32_e32 v76, v92, v76
	v_exp_f32_e32 v74, v74
	v_add_f32_e32 v76, v79, v76
	v_exp_f32_e32 v75, v75
	v_exp_f32_e32 v94, v77
	v_fmamk_f32 v77, v174, 0x3fb8aa3b, v245
	v_add_f32_e32 v76, v72, v76
	v_add_f32_e32 v76, v73, v76
	v_exp_f32_e32 v95, v77
	v_fmamk_f32 v77, v175, 0x3fb8aa3b, v245
	v_sub_f32_e32 v82, v226, v84
	v_add_f32_e32 v76, v74, v76
	v_mul_f32_e32 v82, 0x3fb8aa3b, v82
	v_add_f32_e32 v76, v75, v76
	v_exp_f32_e32 v164, v77
	v_exp_f32_e32 v82, v82
	v_add_f32_e32 v76, v93, v76
	v_add_f32_e32 v76, v94, v76
	v_add_f32_e32 v76, v95, v76
	v_add_f32_e32 v85, v164, v76
	v_fmac_f32_e32 v83, v225, v80
	v_fmac_f32_e32 v85, v224, v82
	v_cvt_pk_bf16_f32 v76, v86, v87
	v_cvt_pk_bf16_f32 v77, v88, v89
	v_cvt_pk_bf16_f32 v78, v90, v91
	v_cvt_pk_bf16_f32 v79, v92, v79
	v_cvt_pk_bf16_f32 v72, v72, v73
	v_cvt_pk_bf16_f32 v73, v74, v75
	v_cvt_pk_bf16_f32 v74, v93, v94
	v_cvt_pk_bf16_f32 v75, v95, v164
	s_setprio 1
	v_add3_u32 v240, s28, v198, v197
	ds_read_b64_tr_b16 v[164:165], v240 offset:16384
	ds_read_b64_tr_b16 v[166:167], v240 offset:20480
	ds_read_b64_tr_b16 v[168:169], v240 offset:24576
	ds_read_b64_tr_b16 v[170:171], v240 offset:28672
	v_add3_u32 v241, s28, v199, v197
	ds_read_b64_tr_b16 v[172:173], v241 offset:16384
	ds_read_b64_tr_b16 v[174:175], v241 offset:20480
	v_pk_mul_f32 v[60:61], v[60:61], v[80:81] op_sel_hi:[1,0]
	v_pk_mul_f32 v[62:63], v[62:63], v[80:81] op_sel_hi:[1,0]
	v_pk_mul_f32 v[28:29], v[28:29], v[82:83] op_sel_hi:[1,0]
	v_pk_mul_f32 v[30:31], v[30:31], v[82:83] op_sel_hi:[1,0]
	s_waitcnt lgkmcnt(4)
	v_mfma_f32_16x16x32_bf16 v[60:63], v[164:167], v[68:71], v[60:63]
	v_mfma_f32_16x16x32_bf16 v[28:31], v[164:167], v[76:79], v[28:31]
	ds_read_b64_tr_b16 v[236:237], v241 offset:24576
	ds_read_b64_tr_b16 v[238:239], v241 offset:28672
	v_pk_mul_f32 v[56:57], v[56:57], v[80:81] op_sel_hi:[1,0]
	v_pk_mul_f32 v[58:59], v[58:59], v[80:81] op_sel_hi:[1,0]
	v_pk_mul_f32 v[24:25], v[24:25], v[82:83] op_sel_hi:[1,0]
	v_pk_mul_f32 v[26:27], v[26:27], v[82:83] op_sel_hi:[1,0]
	s_waitcnt lgkmcnt(4)
; __device__ __forceinline__ f32x4 mfma16(bf16x8 a, bf16x8 b, f32x4 c) { return __builtin_amdgcn_mfma_f32_16x16x32_bf16(a, b, c, 0, 0, 0); }
; __device__ __forceinline__ void b_item(const Params& P, int layer, LAS unsigned char* lds, int item, int tid) {
;     ...
;             __builtin_amdgcn_s_setprio(1);
; #pragma unroll
;             for (int vb = 0; vb < 8; ++vb) { acco[0][vb] = acco[0][vb] * alpha[0]; acco[1][vb] = acco[1][vb] * alpha[1];
; #pragma unroll
;                 for (int ks = 0; ks < 2; ++ks) { const bf16x8 vf = tr_frag_a<true>(Vt, vaddr[vb], ks);
;                     acco[0][vb] = mfma16(vf, pf[0][ks], acco[0][vb]); acco[1][vb] = mfma16(vf, pf[1][ks], acco[1][vb]); } }
;             __builtin_amdgcn_s_setprio(0);
	v_mfma_f32_16x16x32_bf16 v[60:63], v[168:171], v[64:67], v[60:63]
	v_mfma_f32_16x16x32_bf16 v[28:31], v[168:171], v[72:75], v[28:31]
	v_add3_u32 v240, s28, v200, v197
	ds_read_b64_tr_b16 v[164:165], v240 offset:16384
	ds_read_b64_tr_b16 v[166:167], v240 offset:20480
	s_waitcnt lgkmcnt(4)
	v_mfma_f32_16x16x32_bf16 v[56:59], v[172:175], v[68:71], v[56:59]
	v_mfma_f32_16x16x32_bf16 v[24:27], v[172:175], v[76:79], v[24:27]
	ds_read_b64_tr_b16 v[168:169], v240 offset:24576
	ds_read_b64_tr_b16 v[170:171], v240 offset:28672
	v_pk_mul_f32 v[52:53], v[52:53], v[80:81] op_sel_hi:[1,0]
	v_pk_mul_f32 v[54:55], v[54:55], v[80:81] op_sel_hi:[1,0]
	v_pk_mul_f32 v[20:21], v[20:21], v[82:83] op_sel_hi:[1,0]
	v_pk_mul_f32 v[22:23], v[22:23], v[82:83] op_sel_hi:[1,0]
	s_waitcnt lgkmcnt(4)
	v_mfma_f32_16x16x32_bf16 v[56:59], v[236:239], v[64:67], v[56:59]
	v_mfma_f32_16x16x32_bf16 v[24:27], v[236:239], v[72:75], v[24:27]
	v_add3_u32 v241, s28, v201, v197
	ds_read_b64_tr_b16 v[172:173], v241 offset:16384
	ds_read_b64_tr_b16 v[174:175], v241 offset:20480
	s_waitcnt lgkmcnt(4)
	v_mfma_f32_16x16x32_bf16 v[52:55], v[164:167], v[68:71], v[52:55]
	v_mfma_f32_16x16x32_bf16 v[20:23], v[164:167], v[76:79], v[20:23]
	ds_read_b64_tr_b16 v[236:237], v241 offset:24576
	ds_read_b64_tr_b16 v[238:239], v241 offset:28672
	v_pk_mul_f32 v[48:49], v[48:49], v[80:81] op_sel_hi:[1,0]
	v_pk_mul_f32 v[50:51], v[50:51], v[80:81] op_sel_hi:[1,0]
	v_pk_mul_f32 v[16:17], v[16:17], v[82:83] op_sel_hi:[1,0]
	v_pk_mul_f32 v[18:19], v[18:19], v[82:83] op_sel_hi:[1,0]
	s_waitcnt lgkmcnt(4)
	v_mfma_f32_16x16x32_bf16 v[52:55], v[168:171], v[64:67], v[52:55]
	v_mfma_f32_16x16x32_bf16 v[20:23], v[168:171], v[72:75], v[20:23]
	v_add3_u32 v240, s28, v202, v197
	ds_read_b64_tr_b16 v[164:165], v240 offset:16384
	ds_read_b64_tr_b16 v[166:167], v240 offset:20480
	s_waitcnt lgkmcnt(4)
	v_mfma_f32_16x16x32_bf16 v[48:51], v[172:175], v[68:71], v[48:51]
	v_mfma_f32_16x16x32_bf16 v[16:19], v[172:175], v[76:79], v[16:19]
	ds_read_b64_tr_b16 v[168:169], v240 offset:24576
	ds_read_b64_tr_b16 v[170:171], v240 offset:28672
	v_pk_mul_f32 v[44:45], v[44:45], v[80:81] op_sel_hi:[1,0]
	v_pk_mul_f32 v[46:47], v[46:47], v[80:81] op_sel_hi:[1,0]
	v_pk_mul_f32 v[12:13], v[12:13], v[82:83] op_sel_hi:[1,0]
	v_pk_mul_f32 v[14:15], v[14:15], v[82:83] op_sel_hi:[1,0]
	s_waitcnt lgkmcnt(4)
	v_mfma_f32_16x16x32_bf16 v[48:51], v[236:239], v[64:67], v[48:51]
	v_mfma_f32_16x16x32_bf16 v[16:19], v[236:239], v[72:75], v[16:19]
	v_add3_u32 v241, s28, v203, v197
	ds_read_b64_tr_b16 v[172:173], v241 offset:16384
	ds_read_b64_tr_b16 v[174:175], v241 offset:20480
	s_waitcnt lgkmcnt(4)
	v_mfma_f32_16x16x32_bf16 v[44:47], v[164:167], v[68:71], v[44:47]
	v_mfma_f32_16x16x32_bf16 v[12:15], v[164:167], v[76:79], v[12:15]
	ds_read_b64_tr_b16 v[236:237], v241 offset:24576
	ds_read_b64_tr_b16 v[238:239], v241 offset:28672
	v_pk_mul_f32 v[40:41], v[40:41], v[80:81] op_sel_hi:[1,0]
	v_pk_mul_f32 v[42:43], v[42:43], v[80:81] op_sel_hi:[1,0]
	v_pk_mul_f32 v[8:9], v[8:9], v[82:83] op_sel_hi:[1,0]
	v_pk_mul_f32 v[10:11], v[10:11], v[82:83] op_sel_hi:[1,0]
	s_waitcnt lgkmcnt(4)
	v_mfma_f32_16x16x32_bf16 v[44:47], v[168:171], v[64:67], v[44:47]
	v_mfma_f32_16x16x32_bf16 v[12:15], v[168:171], v[72:75], v[12:15]
	v_add3_u32 v240, s28, v204, v197
	ds_read_b64_tr_b16 v[164:165], v240 offset:16384
	ds_read_b64_tr_b16 v[166:167], v240 offset:20480
	s_waitcnt lgkmcnt(4)
	v_mfma_f32_16x16x32_bf16 v[40:43], v[172:175], v[68:71], v[40:43]
	v_mfma_f32_16x16x32_bf16 v[8:11], v[172:175], v[76:79], v[8:11]
	ds_read_b64_tr_b16 v[168:169], v240 offset:24576
	ds_read_b64_tr_b16 v[170:171], v240 offset:28672
	v_pk_mul_f32 v[36:37], v[36:37], v[80:81] op_sel_hi:[1,0]
	v_pk_mul_f32 v[38:39], v[38:39], v[80:81] op_sel_hi:[1,0]
	v_pk_mul_f32 v[4:5], v[4:5], v[82:83] op_sel_hi:[1,0]
	v_pk_mul_f32 v[6:7], v[6:7], v[82:83] op_sel_hi:[1,0]
	s_waitcnt lgkmcnt(4)
	v_mfma_f32_16x16x32_bf16 v[40:43], v[236:239], v[64:67], v[40:43]
	v_mfma_f32_16x16x32_bf16 v[8:11], v[236:239], v[72:75], v[8:11]
	v_add3_u32 v241, s28, v205, v197
	ds_read_b64_tr_b16 v[172:173], v241 offset:16384
	ds_read_b64_tr_b16 v[174:175], v241 offset:20480
	s_waitcnt lgkmcnt(4)
	v_mfma_f32_16x16x32_bf16 v[36:39], v[164:167], v[68:71], v[36:39]
	v_mfma_f32_16x16x32_bf16 v[4:7], v[164:167], v[76:79], v[4:7]
	ds_read_b64_tr_b16 v[236:237], v241 offset:24576
	ds_read_b64_tr_b16 v[238:239], v241 offset:28672
	v_pk_mul_f32 v[32:33], v[32:33], v[80:81] op_sel_hi:[1,0]
	v_pk_mul_f32 v[34:35], v[34:35], v[80:81] op_sel_hi:[1,0]
	v_pk_mul_f32 v[0:1], v[0:1], v[82:83] op_sel_hi:[1,0]
	v_pk_mul_f32 v[2:3], v[2:3], v[82:83] op_sel_hi:[1,0]
	s_waitcnt lgkmcnt(4)
	v_mfma_f32_16x16x32_bf16 v[36:39], v[168:171], v[64:67], v[36:39]
	v_mfma_f32_16x16x32_bf16 v[4:7], v[168:171], v[72:75], v[4:7]
	s_waitcnt lgkmcnt(2)
	v_mfma_f32_16x16x32_bf16 v[32:35], v[172:175], v[68:71], v[32:35]
	v_mfma_f32_16x16x32_bf16 v[0:3], v[172:175], v[76:79], v[0:3]
	s_waitcnt lgkmcnt(0)
	v_mfma_f32_16x16x32_bf16 v[32:35], v[236:239], v[64:67], v[32:35]
	v_mfma_f32_16x16x32_bf16 v[0:3], v[236:239], v[72:75], v[0:3]
	s_setprio 0
	v_mov_b32_e32 v227, v81
	v_mov_b32_e32 v226, v84
	v_mov_b32_e32 v224, v85
	v_mov_b32_e32 v225, v83

; __device__ __forceinline__ void b_item(const Params& P, int layer, LAS unsigned char* lds, int item, int tid) {
;     ...
;             for (int u = 0; u < 2; ++u) { const int t = 32 * th + 16 * u + c15; float mt = -1e30f;
; #pragma unroll
;                 for (int sb = 0; sb < 4; ++sb) {
;                     if (dl >= 192) {
; #pragma unroll
;                         for (int r = 0; r < 4; ++r) { const float xv = accs[u][sb][r] * 0.08838834764831845f + bfar; accs[u][sb][r] = xv; mt = fmaxf(mt, xv); }
;                     } else {
; #pragma unroll
;                         for (int r = 0; r < 4; ++r) { const int s = 16 * sb + 4 * g + r; int rel = t - s + dl; rel = rel > 128 ? 128 : rel;
;                             const float xv = accs[u][sb][r] * 0.08838834764831845f + bias[rel + 128]; accs[u][sb][r] = xv; mt = fmaxf(mt, xv); } } }
;                 mt = fmaxf(mt, __shfl_xor(mt, 16)); mt = fmaxf(mt, __shfl_xor(mt, 32));
.LBB0_180:
	s_or_b64 exec, exec, s[0:1]
	v_mov_b32_e32 v80, v168
	v_mov_b32_e32 v81, v168
	s_nop 1
	v_permlane16_swap_b32 v80, v81
	v_max_f32_e32 v80, v80, v81
	v_mov_b32_e32 v81, v80
	v_mov_b32_e32 v83, v80
	s_nop 1
	v_permlane32_swap_b32 v81, v83
	v_max_f32_e32 v81, v81, v83
	s_and_saveexec_b64 s[0:1], vcc
	s_xor_b64 s[0:1], exec, s[0:1]
	s_cbranch_execz .LBB0_182
	v_add_u32_e32 v83, 0x210, v172
	v_add_u32_e32 v169, 0x20f, v172
	v_min_i32_e32 v168, 0x80, v83
	v_min_i32_e32 v169, 0x80, v169
	v_lshl_add_u32 v168, v168, 2, s74
	v_lshl_add_u32 v169, v169, 2, s74
	ds_read_b32 v168, v168 offset:512
	ds_read_b32 v169, v169 offset:512
	v_min_i32_e32 v244, 0x82, v83
	v_min_i32_e32 v245, 0x83, v83
	v_lshl_add_u32 v244, v244, 2, s74
	v_lshl_add_u32 v245, v245, 2, s74
	ds_read_b32 v244, v244 offset:504
	ds_read_b32 v245, v245 offset:500
	s_waitcnt lgkmcnt(2)
	v_pk_fma_f32 v[168:169], v[76:77], s[34:35], v[168:169] op_sel_hi:[1,0,1]
	v_max3_f32 v173, v168, s96, v169
	s_waitcnt lgkmcnt(0)
	v_pk_fma_f32 v[170:171], v[78:79], s[34:35], v[244:245] op_sel_hi:[1,0,1]
	s_nop 0
	v_max3_f32 v173, v173, v170, v171
	s_andn2_saveexec_b64 s[0:1], s[0:1]
	s_branch .LBB0_183
